# remove dead WINROWS f32 stores in in-proj epilogue (exec-masked)
# speedup vs baseline: 1.0068x; 1.0068x over previous
;     DI void operator()(const f32x4 (&acc)[2][2][4][2], const pg8::Unit& u, int wr, int wc, int fr, int fq) const {
;     ...
;         const int which = pn - 16;
;         const bool dorope = (pn < 16) || ((which & 1) == 0);
; #pragma unroll
;         for (int ai = 0; ai < 2; ++ai)
; #pragma unroll
;             for (int m = 0; m < 4; ++m) {
;                 const int row = row0 + ai * 128 + m * 16;
;                 const bool samp = row >= MP;
;                 const int srow = row - MP;
;                 const int pos = samp ? (TT + (srow & 7)) : (row & (TT - 1));
;                 float cs[4], sn[4];
; #pragma unroll
;                 for (int i = 0; i < 4; ++i) { float rev = (float)pos * frev[i]; rev = rev - floorf(rev); cs[i] = __builtin_amdgcn_cosf(rev); sn[i] = __builtin_amdgcn_sinf(rev); }
; #pragma unroll
;                 for (int bj = 0; bj < 2; ++bj) {
;                     f32x4 x1 = acc[ai][bj][m][0], x2 = acc[ai][bj][m][1], o1, o2;
;                     if (dorope) {
; #pragma unroll
;                         for (int i = 0; i < 4; ++i) { o1[i] = x1[i] * cs[i] - x2[i] * sn[i]; o2[i] = x2[i] * cs[i] + x1[i] * sn[i]; }
;                     } else { o1 = x1; o2 = x2; }
;                     const int hh = 2 * bj + (wc >> 1);
;                     if (pn < 16) {
;                         const int head = (pn - 12) * 4 + hh;
;                         bf16* q = nq + (size_t)row * 1024 + head * 64 + dlo;
;                         u32x2 w1, w2; w1.x = pk2(o1[0] * 0.125f, o1[1] * 0.125f); w1.y = pk2(o1[2] * 0.125f, o1[3] * 0.125f); w2.x = pk2(o2[0] * 0.125f, o2[1] * 0.125f); w2.y = pk2(o2[2] * 0.125f, o2[3] * 0.125f);
;                         *(u32x2*)q = w1; *(u32x2*)(q + 32) = w2;
;                     } else {
;                         const int br = which >> 1, kvsel = which & 1;
;                         const int inrow = kvsel * 256 + hh * 64 + dlo;
;                         float* dst;
;                         if (br == 0) dst = out + (samp ? O_CMPS + (size_t)srow * 512 : O_CMPP + (size_t)row * 512);
;                         else if (br == 1) dst = out + (samp ? O_SLCS + (size_t)srow * 512 : O_SLCP + (size_t)row * 512);
;                         else dst = samp ? out + O_WINS + ((size_t)(srow >> 3) * 512 + 504 + (srow & 7)) * 512 : winrows + (size_t)row * 512;
.LBB0_495:
	s_mov_b64 s[98:99], -1
	s_lshl_b32 s8, s2, 8
	s_add_i32 s8, s8, s23
	v_or_b32_e32 v158, s8, v147
	s_cmp_gt_i32 s60, 11
	s_mov_b64 s[2:3], -1
	s_cbranch_scc0 .LBB0_518
	v_sub_co_u32_e64 v130, s[2:3], s60, 16
	s_xor_b64 s[6:7], s[2:3], -1
	s_and_b32 s65, s60, 1
	s_cmp_eq_u32 s65, 0
	s_cselect_b64 s[70:71], -1, 0
	s_or_b64 s[72:73], s[2:3], s[70:71]
	s_movk_i32 s2, 0x4000
	v_cmp_gt_i32_e64 s[10:11], s2, v158
	s_movk_i32 s2, 0x3fff
	v_cmp_lt_i32_e64 s[2:3], s2, v158
	v_and_b32_e32 v160, 0x7cf, v158
	v_readfirstlane_b32 s9, v130
	v_cndmask_b32_e64 v130, v160, v194, s[2:3]
	v_cvt_f32_u32_e32 v130, v130
	s_mov_b32 s22, s96
	s_andn2_b64 vcc, exec, s[72:73]
	v_mov_b32_e32 v132, v124
	v_mul_f32_e32 v131, v190, v130
	v_floor_f32_e32 v131, v131
	v_fma_f32 v131, v190, v130, -v131
	v_cos_f32_e32 v168, v131
	v_sin_f32_e32 v162, v131
	v_mul_f32_e32 v131, v191, v130
	v_floor_f32_e32 v131, v131
	v_fma_f32 v131, v191, v130, -v131
	v_cos_f32_e32 v169, v131
	v_sin_f32_e32 v163, v131
	v_mul_f32_e32 v131, v192, v130
	v_floor_f32_e32 v131, v131
	v_fma_f32 v131, v192, v130, -v131
	v_cos_f32_e32 v186, v131
	v_sin_f32_e32 v187, v131
	v_mul_f32_e32 v131, v193, v130
	v_floor_f32_e32 v131, v131
	v_fma_f32 v130, v193, v130, -v131
	v_cos_f32_e32 v170, v130
	v_sin_f32_e32 v171, v130
	v_cndmask_b32_e64 v130, 0, 1, s[72:73]
	v_cmp_ne_u32_e64 s[4:5], 1, v130
	v_mov_b32_e32 v130, v122
	v_mov_b32_e32 v131, v123
	v_mov_b32_e32 v133, v125
	v_mov_b32_e32 v134, v126
	v_mov_b32_e32 v135, v127
	v_mov_b32_e32 v136, v128
	v_mov_b32_e32 v137, v129
	s_cbranch_vccnz .LBB0_498
	v_mov_b32_e32 v174, v129
	v_mov_b32_e32 v175, v125
	v_pk_mul_f32 v[130:131], v[162:163], v[122:123]
	v_pk_mul_f32 v[134:135], v[170:171], v[174:175]
	v_pk_mul_f32 v[132:133], v[168:169], v[122:123]
	v_mov_b32_e32 v137, v134
	v_mov_b32_e32 v165, v135
	v_pk_fma_f32 v[134:135], v[168:169], v[126:127], v[130:131] neg_lo:[0,0,1] neg_hi:[0,0,1]
	v_mov_b32_e32 v130, v171
	v_mov_b32_e32 v131, v170
	v_pk_mul_f32 v[130:131], v[130:131], v[174:175]
	v_mul_f32_e32 v136, v186, v128
	v_mul_f32_e32 v164, v187, v124
	v_mul_f32_e32 v166, v186, v124
	v_mul_f32_e32 v172, v187, v128
	v_mov_b32_e32 v173, v130
	v_mov_b32_e32 v167, v131
	v_pk_add_f32 v[136:137], v[136:137], v[164:165] neg_lo:[0,1] neg_hi:[0,1]
	v_pk_fma_f32 v[130:131], v[162:163], v[126:127], v[132:133]
	v_pk_add_f32 v[132:133], v[172:173], v[166:167]
.LBB0_498:
	s_lshr_b32 s18, s9, 1
	s_cmp_lt_u32 s9, 2
	s_cselect_b64 s[76:77], -1, 0
	s_cmp_gt_u32 s9, 1
	s_cselect_b64 s[74:75], -1, 0
	s_cmp_lg_u32 s18, 1
	s_cselect_b64 s[72:73], -1, 0
	s_cmp_lg_u32 s18, 2
	s_cselect_b64 s[78:79], -1, 0
	s_lshl_b64 s[80:81], s[18:19], 5
	s_add_u32 s80, s80, 0xffffffe0
	s_addc_u32 s81, s81, -1
	s_ashr_i32 s82, s8, 11
	s_ashr_i32 s9, s8, 9
	s_ashr_i32 s83, s82, 31
	s_and_b32 s12, s9, -4
	s_lshl_b64 s[84:85], s[82:83], 20
	s_ashr_i32 s9, s12, 31
	s_add_u32 s82, s80, s12
	v_add_u32_e32 v164, 0xffffc000, v158
	s_addc_u32 s83, s81, s9
	v_ashrrev_i32_e32 v159, 31, v158
	v_lshrrev_b32_e32 v142, 3, v164
	v_mov_b32_e32 v165, v143
	s_lshr_b32 s8, s8, 4
	v_lshl_or_b32 v200, s65, 8, v146
	s_mul_i32 s65, s65, 0x11000
	v_lshlrev_b64 v[178:179], 11, v[158:159]
	v_lshlrev_b64 v[176:177], 18, v[142:143]
	v_lshlrev_b64 v[166:167], 9, v[158:159]
	v_lshlrev_b64 v[180:181], 9, v[164:165]
	s_nor_b64 s[86:87], s[78:79], s[2:3]
	v_cmp_lt_u32_e32 vcc, s13, v160
	v_lshlrev_b32_e32 v159, 6, v158
	s_and_b32 s8, s8, 0x7c
	s_addk_i32 s12, 0x200
	v_or_b32_e32 v176, v176, v148
	v_lshl_add_u64 v[172:173], v[166:167], 0, s[50:51]
	v_lshl_add_u64 v[174:175], v[180:181], 0, s[52:53]
	v_lshl_add_u64 v[164:165], v[166:167], 0, s[54:55]
	v_lshl_add_u64 v[166:167], v[180:181], 0, s[56:57]
	s_and_b64 s[90:91], s[86:87], vcc
	v_lshlrev_b32_e32 v142, 9, v160
	s_nor_b64 s[88:89], s[76:77], s[2:3]
	v_and_b32_e32 v159, 0x1f3c0, v159
	s_nor_b64 s[86:87], s[74:75], s[2:3]
	s_or_b32 s96, s8, s65
	s_and_b64 vcc, exec, s[6:7]
	s_cbranch_vccz .LBB0_520
	s_mov_b64 s[8:9], -1
	s_and_b64 vcc, exec, s[74:75]
	s_cbranch_vccz .LBB0_509
	s_and_b64 vcc, exec, s[72:73]
	s_cbranch_vccz .LBB0_506
	s_and_saveexec_b64 s[8:9], s[10:11]
	s_xor_b64 s[8:9], exec, s[8:9]
	s_mov_b64 s[98:99], s[8:9]
	s_cbranch_execz .LBB0_503
	v_readlane_b32 s30, v254, 17
	v_readlane_b32 s31, v254, 18
	s_nop 1
	v_lshl_add_u64 v[160:161], s[30:31], 0, v[178:179]

;     DI void operator()(const f32x4 (&acc)[2][2][4][2], const pg8::Unit& u, int wr, int wc, int fr, int fq) const {
;     ...
;                         if (br == 0) dst = out + (samp ? O_CMPS + (size_t)srow * 512 : O_CMPP + (size_t)row * 512);
;                         else if (br == 1) dst = out + (samp ? O_SLCS + (size_t)srow * 512 : O_SLCP + (size_t)row * 512);
;                         else dst = samp ? out + O_WINS + ((size_t)(srow >> 3) * 512 + 504 + (srow & 7)) * 512 : winrows + (size_t)row * 512;
;                         *(f32x4*)(dst + inrow) = o1; *(f32x4*)(dst + inrow + 32) = o2;
;                         if (br == 2 && !samp && (row & (TT - 1)) >= TT - 512) {
;                             float* d2 = out + O_WINP + ((size_t)(row >> 11) * 512 + (row & (TT - 1)) - (TT - 512)) * 512 + inrow;
;                             *(f32x4*)d2 = o1; *(f32x4*)(d2 + 32) = o2;
.LBB0_511:
	v_or_b32_e32 v180, s21, v200
	v_lshlrev_b32_e32 v180, 2, v180
	v_mov_b32_e32 v181, v143
	v_lshl_add_u64 v[160:161], v[160:161], 0, v[180:181]
	s_mov_b64 s[100:101], exec
	s_and_b64 exec, exec, s[98:99]
	global_store_dwordx4 v[160:161], v[134:137], off
	global_store_dwordx4 v[160:161], v[130:133], off offset:128
	s_mov_b64 exec, s[100:101]
	s_mov_b64 s[98:99], -1
	s_and_saveexec_b64 s[8:9], s[90:91]
	s_cbranch_execz .LBB0_513
	s_add_u32 s92, s40, s84
	s_addc_u32 s93, s41, s85
	v_lshl_add_u64 v[160:161], v[142:143], 2, s[92:93]
	v_lshl_add_u64 v[160:161], v[160:161], 0, v[180:181]
	global_store_dwordx4 v[160:161], v[134:137], off
	global_store_dwordx4 v[160:161], v[130:133], off offset:128

;     DI void operator()(const f32x4 (&acc)[2][2][4][2], const pg8::Unit& u, int wr, int wc, int fr, int fq) const {
;     ...
;                         const int br = which >> 1, kvsel = which & 1;
;                         const int inrow = kvsel * 256 + hh * 64 + dlo;
;                         float* dst;
;                         if (br == 0) dst = out + (samp ? O_CMPS + (size_t)srow * 512 : O_CMPP + (size_t)row * 512);
;                         else if (br == 1) dst = out + (samp ? O_SLCS + (size_t)srow * 512 : O_SLCP + (size_t)row * 512);
;                         else dst = samp ? out + O_WINS + ((size_t)(srow >> 3) * 512 + 504 + (srow & 7)) * 512 : winrows + (size_t)row * 512;
.LBB0_527:
	v_cndmask_b32_e64 v161, 0, 1, s[6:7]
	v_cmp_ne_u32_e64 s[8:9], 1, v161
	v_cndmask_b32_e64 v161, 0, 1, s[74:75]
	s_andn2_b64 vcc, exec, s[6:7]
	v_cmp_ne_u32_e64 s[6:7], 1, v161
	s_cbranch_vccnz .LBB0_547
	s_and_b64 vcc, exec, s[6:7]
	s_mov_b64 s[92:93], -1
	s_cbranch_vccnz .LBB0_538
	s_andn2_b64 vcc, exec, s[72:73]
	s_cbranch_vccnz .LBB0_535
	s_and_saveexec_b64 s[92:93], s[10:11]
	s_xor_b64 s[10:11], exec, s[92:93]
	s_mov_b64 s[98:99], s[10:11]
	s_cbranch_execz .LBB0_532
	v_readlane_b32 s30, v254, 17
	v_readlane_b32 s31, v254, 18
	s_nop 1
	v_lshl_add_u64 v[162:163], s[30:31], 0, v[178:179]

;     DI void operator()(const f32x4 (&acc)[2][2][4][2], const pg8::Unit& u, int wr, int wc, int fr, int fq) const {
;     ...
;                         if (br == 0) dst = out + (samp ? O_CMPS + (size_t)srow * 512 : O_CMPP + (size_t)row * 512);
;                         else if (br == 1) dst = out + (samp ? O_SLCS + (size_t)srow * 512 : O_SLCP + (size_t)row * 512);
;                         else dst = samp ? out + O_WINS + ((size_t)(srow >> 3) * 512 + 504 + (srow & 7)) * 512 : winrows + (size_t)row * 512;
;                         *(f32x4*)(dst + inrow) = o1; *(f32x4*)(dst + inrow + 32) = o2;
;                         if (br == 2 && !samp && (row & (TT - 1)) >= TT - 512) {
;                             float* d2 = out + O_WINP + ((size_t)(row >> 11) * 512 + (row & (TT - 1)) - (TT - 512)) * 512 + inrow;
;                             *(f32x4*)d2 = o1; *(f32x4*)(d2 + 32) = o2;
.LBB0_540:
	v_or_b32_e32 v161, s28, v200
	v_lshlrev_b32_e32 v164, 2, v161
	v_mov_b32_e32 v165, v143
	v_lshl_add_u64 v[162:163], v[162:163], 0, v[164:165]
	s_mov_b64 s[100:101], exec
	s_and_b64 exec, exec, s[98:99]
	global_store_dwordx4 v[162:163], v[134:137], off
	global_store_dwordx4 v[162:163], v[130:133], off offset:128
	s_mov_b64 exec, s[100:101]
	s_mov_b64 s[98:99], -1
	s_and_saveexec_b64 s[2:3], s[90:91]
	s_cbranch_execz .LBB0_542
	s_add_u32 s10, s40, s84
	s_addc_u32 s11, s41, s85
	v_lshl_add_u64 v[162:163], v[142:143], 2, s[10:11]
	v_lshl_add_u64 v[162:163], v[162:163], 0, v[164:165]
	global_store_dwordx4 v[162:163], v[134:137], off
	global_store_dwordx4 v[162:163], v[130:133], off offset:128

; DI unsigned pk2(float lo, float hi) { f32x2 v = {lo, hi}; bf16x2_t b = __builtin_convertvector(v, bf16x2_t); return __builtin_bit_cast(unsigned, b); }
;     DI void operator()(const f32x4 (&acc)[2][2][4][2], const pg8::Unit& u, int wr, int wc, int fr, int fq) const {
;     ...
;                 const int row = row0 + ai * 128 + m * 16;
;                 const bool samp = row >= MP;
;                 const int srow = row - MP;
;                 const int pos = samp ? (TT + (srow & 7)) : (row & (TT - 1));
;                 float cs[4], sn[4];
; #pragma unroll
;                 for (int i = 0; i < 4; ++i) { float rev = (float)pos * frev[i]; rev = rev - floorf(rev); cs[i] = __builtin_amdgcn_cosf(rev); sn[i] = __builtin_amdgcn_sinf(rev); }
; #pragma unroll
;                 for (int bj = 0; bj < 2; ++bj) {
;                     f32x4 x1 = acc[ai][bj][m][0], x2 = acc[ai][bj][m][1], o1, o2;
;                     if (dorope) {
; #pragma unroll
;                         for (int i = 0; i < 4; ++i) { o1[i] = x1[i] * cs[i] - x2[i] * sn[i]; o2[i] = x2[i] * cs[i] + x1[i] * sn[i]; }
;                     } else { o1 = x1; o2 = x2; }
;                     const int hh = 2 * bj + (wc >> 1);
;                     if (pn < 16) {
;                         const int head = (pn - 12) * 4 + hh;
;                         bf16* q = nq + (size_t)row * 1024 + head * 64 + dlo;
;                         u32x2 w1, w2; w1.x = pk2(o1[0] * 0.125f, o1[1] * 0.125f); w1.y = pk2(o1[2] * 0.125f, o1[3] * 0.125f); w2.x = pk2(o2[0] * 0.125f, o2[1] * 0.125f); w2.y = pk2(o2[2] * 0.125f, o2[3] * 0.125f);
;                         *(u32x2*)q = w1; *(u32x2*)(q + 32) = w2;
;                     } else {
;                         const int br = which >> 1, kvsel = which & 1;
;                         const int inrow = kvsel * 256 + hh * 64 + dlo;
;                         float* dst;
;                         if (br == 0) dst = out + (samp ? O_CMPS + (size_t)srow * 512 : O_CMPP + (size_t)row * 512);
;                         else if (br == 1) dst = out + (samp ? O_SLCS + (size_t)srow * 512 : O_SLCP + (size_t)row * 512);
;                         else dst = samp ? out + O_WINS + ((size_t)(srow >> 3) * 512 + 504 + (srow & 7)) * 512 : winrows + (size_t)row * 512;
.LBB0_553:
	v_add_u32_e32 v162, 0xffffc010, v158
	v_lshrrev_b32_e32 v142, 3, v162
	v_lshlrev_b64 v[174:175], 18, v[142:143]
	v_cmp_lt_u32_e32 vcc, s13, v159
	v_lshlrev_b32_e32 v142, 9, v159
	v_lshlrev_b32_e32 v159, 6, v180
	v_ashrrev_i32_e32 v181, 31, v180
	v_mov_b32_e32 v163, v143
	v_and_b32_e32 v186, 0x1f7c0, v159
	v_lshrrev_b32_e32 v159, 4, v180
	v_lshlrev_b64 v[164:165], 9, v[180:181]
	v_lshlrev_b64 v[182:183], 9, v[162:163]
	s_nor_b64 s[86:87], s[78:79], s[2:3]
	v_and_b32_e32 v159, 0x7d, v159
	v_lshlrev_b64 v[178:179], 11, v[180:181]
	v_or_b32_e32 v174, v174, v148
	v_lshl_add_u64 v[166:167], v[164:165], 0, s[50:51]
	v_lshl_add_u64 v[168:169], v[182:183], 0, s[52:53]
	v_lshl_add_u64 v[162:163], v[164:165], 0, s[54:55]
	v_lshl_add_u64 v[164:165], v[182:183], 0, s[56:57]
	s_and_b64 s[90:91], s[86:87], vcc
	s_nor_b64 s[88:89], s[76:77], s[2:3]
	s_nor_b64 s[86:87], s[74:75], s[2:3]
	s_and_b64 vcc, exec, s[8:9]
	v_or_b32_e32 v159, s65, v159
	s_cbranch_vccnz .LBB0_573
	s_and_b64 vcc, exec, s[6:7]
	s_mov_b64 s[92:93], -1
	s_cbranch_vccnz .LBB0_564
	s_andn2_b64 vcc, exec, s[72:73]
	s_cbranch_vccnz .LBB0_561
	s_and_saveexec_b64 s[92:93], s[10:11]
	s_xor_b64 s[92:93], exec, s[92:93]
	s_mov_b64 s[98:99], s[92:93]
	s_cbranch_execz .LBB0_558
	v_readlane_b32 s30, v254, 17
	v_readlane_b32 s31, v254, 18
	s_nop 1
	v_lshl_add_u64 v[180:181], s[30:31], 0, v[178:179]

;     DI void operator()(const f32x4 (&acc)[2][2][4][2], const pg8::Unit& u, int wr, int wc, int fr, int fq) const {
;     ...
;                         if (br == 0) dst = out + (samp ? O_CMPS + (size_t)srow * 512 : O_CMPP + (size_t)row * 512);
;                         else if (br == 1) dst = out + (samp ? O_SLCS + (size_t)srow * 512 : O_SLCP + (size_t)row * 512);
;                         else dst = samp ? out + O_WINS + ((size_t)(srow >> 3) * 512 + 504 + (srow & 7)) * 512 : winrows + (size_t)row * 512;
;                         *(f32x4*)(dst + inrow) = o1; *(f32x4*)(dst + inrow + 32) = o2;
;                         if (br == 2 && !samp && (row & (TT - 1)) >= TT - 512) {
;                             float* d2 = out + O_WINP + ((size_t)(row >> 11) * 512 + (row & (TT - 1)) - (TT - 512)) * 512 + inrow;
;                             *(f32x4*)d2 = o1; *(f32x4*)(d2 + 32) = o2;
.LBB0_566:
	v_or_b32_e32 v161, s21, v200
	v_lshlrev_b32_e32 v182, 2, v161
	v_mov_b32_e32 v183, v143
	v_lshl_add_u64 v[180:181], v[180:181], 0, v[182:183]
	s_mov_b64 s[100:101], exec
	s_and_b64 exec, exec, s[98:99]
	global_store_dwordx4 v[180:181], v[134:137], off
	global_store_dwordx4 v[180:181], v[130:133], off offset:128
	s_mov_b64 exec, s[100:101]
	s_mov_b64 s[98:99], -1
	s_and_saveexec_b64 s[92:93], s[90:91]
	s_cbranch_execz .LBB0_568
	s_add_u32 s94, s40, s84
	s_addc_u32 s95, s41, s85
	v_lshl_add_u64 v[180:181], v[142:143], 2, s[94:95]
	v_lshl_add_u64 v[180:181], v[180:181], 0, v[182:183]
	global_store_dwordx4 v[180:181], v[134:137], off
	global_store_dwordx4 v[180:181], v[130:133], off offset:128

;     DI void operator()(const f32x4 (&acc)[2][2][4][2], const pg8::Unit& u, int wr, int wc, int fr, int fq) const {
;     ...
;                         const int br = which >> 1, kvsel = which & 1;
;                         const int inrow = kvsel * 256 + hh * 64 + dlo;
;                         float* dst;
;                         if (br == 0) dst = out + (samp ? O_CMPS + (size_t)srow * 512 : O_CMPP + (size_t)row * 512);
;                         else if (br == 1) dst = out + (samp ? O_SLCS + (size_t)srow * 512 : O_SLCP + (size_t)row * 512);
;                         else dst = samp ? out + O_WINS + ((size_t)(srow >> 3) * 512 + 504 + (srow & 7)) * 512 : winrows + (size_t)row * 512;
.LBB0_580:
	s_and_b64 vcc, exec, s[8:9]
	s_cbranch_vccnz .LBB0_600
	s_and_b64 vcc, exec, s[6:7]
	s_mov_b64 s[92:93], -1
	s_cbranch_vccnz .LBB0_591
	s_andn2_b64 vcc, exec, s[72:73]
	s_cbranch_vccnz .LBB0_588
	s_and_saveexec_b64 s[92:93], s[10:11]
	s_xor_b64 s[10:11], exec, s[92:93]
	s_mov_b64 s[98:99], s[10:11]
	s_cbranch_execz .LBB0_585
	v_readlane_b32 s30, v254, 17
	v_readlane_b32 s31, v254, 18
	s_nop 1
	v_lshl_add_u64 v[170:171], s[30:31], 0, v[178:179]

;     DI void operator()(const f32x4 (&acc)[2][2][4][2], const pg8::Unit& u, int wr, int wc, int fr, int fq) const {
;     ...
;                         if (br == 0) dst = out + (samp ? O_CMPS + (size_t)srow * 512 : O_CMPP + (size_t)row * 512);
;                         else if (br == 1) dst = out + (samp ? O_SLCS + (size_t)srow * 512 : O_SLCP + (size_t)row * 512);
;                         else dst = samp ? out + O_WINS + ((size_t)(srow >> 3) * 512 + 504 + (srow & 7)) * 512 : winrows + (size_t)row * 512;
;                         *(f32x4*)(dst + inrow) = o1; *(f32x4*)(dst + inrow + 32) = o2;
;                         if (br == 2 && !samp && (row & (TT - 1)) >= TT - 512) {
;                             float* d2 = out + O_WINP + ((size_t)(row >> 11) * 512 + (row & (TT - 1)) - (TT - 512)) * 512 + inrow;
;                             *(f32x4*)d2 = o1; *(f32x4*)(d2 + 32) = o2;
.LBB0_593:
	v_or_b32_e32 v161, s28, v200
	v_lshlrev_b32_e32 v162, 2, v161
	v_mov_b32_e32 v163, v143
	v_lshl_add_u64 v[164:165], v[170:171], 0, v[162:163]
	s_mov_b64 s[100:101], exec
	s_and_b64 exec, exec, s[98:99]
	global_store_dwordx4 v[164:165], v[134:137], off
	global_store_dwordx4 v[164:165], v[130:133], off offset:128
	s_mov_b64 exec, s[100:101]
	s_mov_b64 s[98:99], -1
	s_and_saveexec_b64 s[2:3], s[90:91]
	s_cbranch_execz .LBB0_595
	s_add_u32 s10, s40, s84
	s_addc_u32 s11, s41, s85
	v_lshl_add_u64 v[164:165], v[142:143], 2, s[10:11]
	v_lshl_add_u64 v[162:163], v[164:165], 0, v[162:163]
	global_store_dwordx4 v[162:163], v[134:137], off
	global_store_dwordx4 v[162:163], v[130:133], off offset:128

; DI unsigned pk2(float lo, float hi) { f32x2 v = {lo, hi}; bf16x2_t b = __builtin_convertvector(v, bf16x2_t); return __builtin_bit_cast(unsigned, b); }
;     DI void operator()(const f32x4 (&acc)[2][2][4][2], const pg8::Unit& u, int wr, int wc, int fr, int fq) const {
;     ...
;                 const int row = row0 + ai * 128 + m * 16;
;                 const bool samp = row >= MP;
;                 const int srow = row - MP;
;                 const int pos = samp ? (TT + (srow & 7)) : (row & (TT - 1));
;                 float cs[4], sn[4];
; #pragma unroll
;                 for (int i = 0; i < 4; ++i) { float rev = (float)pos * frev[i]; rev = rev - floorf(rev); cs[i] = __builtin_amdgcn_cosf(rev); sn[i] = __builtin_amdgcn_sinf(rev); }
; #pragma unroll
;                 for (int bj = 0; bj < 2; ++bj) {
;                     f32x4 x1 = acc[ai][bj][m][0], x2 = acc[ai][bj][m][1], o1, o2;
;                     if (dorope) {
; #pragma unroll
;                         for (int i = 0; i < 4; ++i) { o1[i] = x1[i] * cs[i] - x2[i] * sn[i]; o2[i] = x2[i] * cs[i] + x1[i] * sn[i]; }
;                     } else { o1 = x1; o2 = x2; }
;                     const int hh = 2 * bj + (wc >> 1);
;                     if (pn < 16) {
;                         const int head = (pn - 12) * 4 + hh;
;                         bf16* q = nq + (size_t)row * 1024 + head * 64 + dlo;
;                         u32x2 w1, w2; w1.x = pk2(o1[0] * 0.125f, o1[1] * 0.125f); w1.y = pk2(o1[2] * 0.125f, o1[3] * 0.125f); w2.x = pk2(o2[0] * 0.125f, o2[1] * 0.125f); w2.y = pk2(o2[2] * 0.125f, o2[3] * 0.125f);
;                         *(u32x2*)q = w1; *(u32x2*)(q + 32) = w2;
;                     } else {
;                         const int br = which >> 1, kvsel = which & 1;
;                         const int inrow = kvsel * 256 + hh * 64 + dlo;
;                         float* dst;
;                         if (br == 0) dst = out + (samp ? O_CMPS + (size_t)srow * 512 : O_CMPP + (size_t)row * 512);
;                         else if (br == 1) dst = out + (samp ? O_SLCS + (size_t)srow * 512 : O_SLCP + (size_t)row * 512);
;                         else dst = samp ? out + O_WINS + ((size_t)(srow >> 3) * 512 + 504 + (srow & 7)) * 512 : winrows + (size_t)row * 512;
.LBB0_606:
	v_add_u32_e32 v162, 0xffffc020, v158
	v_lshrrev_b32_e32 v142, 3, v162
	v_lshlrev_b64 v[174:175], 18, v[142:143]
	v_cmp_lt_u32_e32 vcc, s13, v159
	v_lshlrev_b32_e32 v142, 9, v159
	v_lshlrev_b32_e32 v159, 6, v180
	v_ashrrev_i32_e32 v181, 31, v180
	v_mov_b32_e32 v163, v143
	v_and_b32_e32 v186, 0x1fbc0, v159
	v_lshrrev_b32_e32 v159, 4, v180
	v_lshlrev_b64 v[164:165], 9, v[180:181]
	v_lshlrev_b64 v[182:183], 9, v[162:163]
	s_nor_b64 s[86:87], s[78:79], s[2:3]
	v_and_b32_e32 v159, 0x7e, v159
	v_lshlrev_b64 v[178:179], 11, v[180:181]
	v_or_b32_e32 v174, v174, v148
	v_lshl_add_u64 v[166:167], v[164:165], 0, s[50:51]
	v_lshl_add_u64 v[168:169], v[182:183], 0, s[52:53]
	v_lshl_add_u64 v[162:163], v[164:165], 0, s[54:55]
	v_lshl_add_u64 v[164:165], v[182:183], 0, s[56:57]
	s_and_b64 s[90:91], s[86:87], vcc
	s_nor_b64 s[88:89], s[76:77], s[2:3]
	s_nor_b64 s[86:87], s[74:75], s[2:3]
	s_and_b64 vcc, exec, s[8:9]
	v_or_b32_e32 v159, s65, v159
	s_cbranch_vccnz .LBB0_626
	s_and_b64 vcc, exec, s[6:7]
	s_mov_b64 s[92:93], -1
	s_cbranch_vccnz .LBB0_617
	s_andn2_b64 vcc, exec, s[72:73]
	s_cbranch_vccnz .LBB0_614
	s_and_saveexec_b64 s[92:93], s[10:11]
	s_xor_b64 s[92:93], exec, s[92:93]
	s_mov_b64 s[98:99], s[92:93]
	s_cbranch_execz .LBB0_611
	v_readlane_b32 s30, v254, 17
	v_readlane_b32 s31, v254, 18
	s_nop 1
	v_lshl_add_u64 v[180:181], s[30:31], 0, v[178:179]

; DI unsigned pk2(float lo, float hi) { f32x2 v = {lo, hi}; bf16x2_t b = __builtin_convertvector(v, bf16x2_t); return __builtin_bit_cast(unsigned, b); }
;     DI void operator()(const f32x4 (&acc)[2][2][4][2], const pg8::Unit& u, int wr, int wc, int fr, int fq) const {
;     ...
;                 const int row = row0 + ai * 128 + m * 16;
;                 const bool samp = row >= MP;
;                 const int srow = row - MP;
;                 const int pos = samp ? (TT + (srow & 7)) : (row & (TT - 1));
;                 float cs[4], sn[4];
; #pragma unroll
;                 for (int i = 0; i < 4; ++i) { float rev = (float)pos * frev[i]; rev = rev - floorf(rev); cs[i] = __builtin_amdgcn_cosf(rev); sn[i] = __builtin_amdgcn_sinf(rev); }
; #pragma unroll
;                 for (int bj = 0; bj < 2; ++bj) {
;                     f32x4 x1 = acc[ai][bj][m][0], x2 = acc[ai][bj][m][1], o1, o2;
;                     if (dorope) {
; #pragma unroll
;                         for (int i = 0; i < 4; ++i) { o1[i] = x1[i] * cs[i] - x2[i] * sn[i]; o2[i] = x2[i] * cs[i] + x1[i] * sn[i]; }
;                     } else { o1 = x1; o2 = x2; }
;                     const int hh = 2 * bj + (wc >> 1);
;                     if (pn < 16) {
;                         const int head = (pn - 12) * 4 + hh;
;                         bf16* q = nq + (size_t)row * 1024 + head * 64 + dlo;
;                         u32x2 w1, w2; w1.x = pk2(o1[0] * 0.125f, o1[1] * 0.125f); w1.y = pk2(o1[2] * 0.125f, o1[3] * 0.125f); w2.x = pk2(o2[0] * 0.125f, o2[1] * 0.125f); w2.y = pk2(o2[2] * 0.125f, o2[3] * 0.125f);
;                         *(u32x2*)q = w1; *(u32x2*)(q + 32) = w2;
;                     } else {
;                         const int br = which >> 1, kvsel = which & 1;
;                         const int inrow = kvsel * 256 + hh * 64 + dlo;
;                         float* dst;
;                         if (br == 0) dst = out + (samp ? O_CMPS + (size_t)srow * 512 : O_CMPP + (size_t)row * 512);
;                         else if (br == 1) dst = out + (samp ? O_SLCS + (size_t)srow * 512 : O_SLCP + (size_t)row * 512);
;                         else dst = samp ? out + O_WINS + ((size_t)(srow >> 3) * 512 + 504 + (srow & 7)) * 512 : winrows + (size_t)row * 512;
.LBB0_659:
	v_add_u32_e32 v162, 0xffffc030, v158
	v_lshrrev_b32_e32 v142, 3, v162
	v_ashrrev_i32_e32 v181, 31, v180
	v_lshlrev_b64 v[174:175], 18, v[142:143]
	v_mov_b32_e32 v163, v143
	v_cmp_lt_u32_e32 vcc, s13, v159
	v_lshlrev_b32_e32 v142, 9, v159
	v_lshlrev_b32_e32 v159, 6, v180
	v_lshlrev_b64 v[164:165], 9, v[180:181]
	v_lshlrev_b64 v[182:183], 9, v[162:163]
	s_nor_b64 s[86:87], s[78:79], s[2:3]
	v_and_b32_e32 v186, 0x1ffc0, v159
	v_bfe_u32 v159, v180, 4, 7
	v_lshlrev_b64 v[178:179], 11, v[180:181]
	v_or_b32_e32 v174, v174, v148
	v_lshl_add_u64 v[166:167], v[164:165], 0, s[50:51]
	v_lshl_add_u64 v[168:169], v[182:183], 0, s[52:53]
	v_lshl_add_u64 v[162:163], v[164:165], 0, s[54:55]
	v_lshl_add_u64 v[164:165], v[182:183], 0, s[56:57]
	s_and_b64 s[90:91], s[86:87], vcc
	s_nor_b64 s[88:89], s[76:77], s[2:3]
	s_nor_b64 s[86:87], s[74:75], s[2:3]
	s_and_b64 vcc, exec, s[8:9]
	v_or_b32_e32 v159, s65, v159
	s_cbranch_vccnz .LBB0_679
	s_and_b64 vcc, exec, s[6:7]
	s_mov_b64 s[92:93], -1
	s_cbranch_vccnz .LBB0_670
	s_andn2_b64 vcc, exec, s[72:73]
	s_cbranch_vccnz .LBB0_667
	s_and_saveexec_b64 s[92:93], s[10:11]
	s_xor_b64 s[92:93], exec, s[92:93]
	s_mov_b64 s[98:99], s[92:93]
	s_cbranch_execz .LBB0_664
	v_readlane_b32 s30, v254, 17
	v_readlane_b32 s31, v254, 18
	s_nop 1
	v_lshl_add_u64 v[180:181], s[30:31], 0, v[178:179]

; DI unsigned pk2(float lo, float hi) { f32x2 v = {lo, hi}; bf16x2_t b = __builtin_convertvector(v, bf16x2_t); return __builtin_bit_cast(unsigned, b); }
;     DI void operator()(const f32x4 (&acc)[2][2][4][2], const pg8::Unit& u, int wr, int wc, int fr, int fq) const {
;     ...
;                 const int row = row0 + ai * 128 + m * 16;
;                 const bool samp = row >= MP;
;                 const int srow = row - MP;
;                 const int pos = samp ? (TT + (srow & 7)) : (row & (TT - 1));
;                 float cs[4], sn[4];
; #pragma unroll
;                 for (int i = 0; i < 4; ++i) { float rev = (float)pos * frev[i]; rev = rev - floorf(rev); cs[i] = __builtin_amdgcn_cosf(rev); sn[i] = __builtin_amdgcn_sinf(rev); }
; #pragma unroll
;                 for (int bj = 0; bj < 2; ++bj) {
;                     f32x4 x1 = acc[ai][bj][m][0], x2 = acc[ai][bj][m][1], o1, o2;
;                     if (dorope) {
; #pragma unroll
;                         for (int i = 0; i < 4; ++i) { o1[i] = x1[i] * cs[i] - x2[i] * sn[i]; o2[i] = x2[i] * cs[i] + x1[i] * sn[i]; }
;                     } else { o1 = x1; o2 = x2; }
;                     const int hh = 2 * bj + (wc >> 1);
;                     if (pn < 16) {
;                         const int head = (pn - 12) * 4 + hh;
;                         bf16* q = nq + (size_t)row * 1024 + head * 64 + dlo;
;                         u32x2 w1, w2; w1.x = pk2(o1[0] * 0.125f, o1[1] * 0.125f); w1.y = pk2(o1[2] * 0.125f, o1[3] * 0.125f); w2.x = pk2(o2[0] * 0.125f, o2[1] * 0.125f); w2.y = pk2(o2[2] * 0.125f, o2[3] * 0.125f);
;                         *(u32x2*)q = w1; *(u32x2*)(q + 32) = w2;
;                     } else {
;                         const int br = which >> 1, kvsel = which & 1;
;                         const int inrow = kvsel * 256 + hh * 64 + dlo;
;                         float* dst;
;                         if (br == 0) dst = out + (samp ? O_CMPS + (size_t)srow * 512 : O_CMPP + (size_t)row * 512);
;                         else if (br == 1) dst = out + (samp ? O_SLCS + (size_t)srow * 512 : O_SLCP + (size_t)row * 512);
;                         else dst = samp ? out + O_WINS + ((size_t)(srow >> 3) * 512 + 504 + (srow & 7)) * 512 : winrows + (size_t)row * 512;
.LBB0_712:
	v_ashrrev_i32_e32 v142, 9, v184
	v_ashrrev_i32_e32 v162, 11, v184
	v_and_b32_e32 v166, -4, v142
	v_ashrrev_i32_e32 v163, 31, v162
	v_ashrrev_i32_e32 v167, 31, v166
	v_lshlrev_b64 v[164:165], 20, v[162:163]
	v_lshl_add_u64 v[162:163], s[80:81], 0, v[166:167]
	v_add_u32_e32 v159, 0x200, v166
	v_add_u32_e32 v166, 0xffffc080, v158
	v_lshrrev_b32_e32 v142, 3, v166
	v_lshlrev_b64 v[180:181], 18, v[142:143]
	v_cmp_lt_u32_e32 vcc, s13, v161
	v_lshlrev_b32_e32 v142, 9, v161
	v_lshlrev_b32_e32 v161, 6, v184
	v_ashrrev_i32_e32 v185, 31, v184
	v_mov_b32_e32 v167, v143
	v_and_b32_e32 v202, 0x1f3c0, v161
	v_lshrrev_b32_e32 v161, 4, v184
	v_lshlrev_b64 v[168:169], 9, v[184:185]
	v_lshlrev_b64 v[186:187], 9, v[166:167]
	s_nor_b64 s[80:81], s[78:79], s[2:3]
	v_and_b32_e32 v161, 0x7c, v161
	v_lshlrev_b64 v[182:183], 11, v[184:185]
	v_or_b32_e32 v180, v180, v148
	v_lshl_add_u64 v[172:173], v[168:169], 0, s[50:51]
	v_lshl_add_u64 v[176:177], v[186:187], 0, s[52:53]
	v_lshl_add_u64 v[166:167], v[168:169], 0, s[54:55]
	v_lshl_add_u64 v[168:169], v[186:187], 0, s[56:57]
	s_and_b64 s[84:85], s[80:81], vcc
	s_nor_b64 s[82:83], s[76:77], s[2:3]
	s_nor_b64 s[80:81], s[74:75], s[2:3]
	s_and_b64 vcc, exec, s[8:9]
	v_or_b32_e32 v201, s65, v161
	s_cbranch_vccnz .LBB0_732
	s_and_b64 vcc, exec, s[6:7]
	s_mov_b64 s[86:87], -1
	s_cbranch_vccnz .LBB0_723
	s_andn2_b64 vcc, exec, s[72:73]
	s_cbranch_vccnz .LBB0_720
	s_and_saveexec_b64 s[86:87], s[10:11]
	s_xor_b64 s[86:87], exec, s[86:87]
	s_mov_b64 s[98:99], s[86:87]
	s_cbranch_execz .LBB0_717
	v_readlane_b32 s30, v254, 17
	v_readlane_b32 s31, v254, 18
	s_nop 1
	v_lshl_add_u64 v[184:185], s[30:31], 0, v[182:183]

;     DI void operator()(const f32x4 (&acc)[2][2][4][2], const pg8::Unit& u, int wr, int wc, int fr, int fq) const {
;     ...
;                         if (br == 0) dst = out + (samp ? O_CMPS + (size_t)srow * 512 : O_CMPP + (size_t)row * 512);
;                         else if (br == 1) dst = out + (samp ? O_SLCS + (size_t)srow * 512 : O_SLCP + (size_t)row * 512);
;                         else dst = samp ? out + O_WINS + ((size_t)(srow >> 3) * 512 + 504 + (srow & 7)) * 512 : winrows + (size_t)row * 512;
;                         *(f32x4*)(dst + inrow) = o1; *(f32x4*)(dst + inrow + 32) = o2;
;                         if (br == 2 && !samp && (row & (TT - 1)) >= TT - 512) {
;                             float* d2 = out + O_WINP + ((size_t)(row >> 11) * 512 + (row & (TT - 1)) - (TT - 512)) * 512 + inrow;
;                             *(f32x4*)d2 = o1; *(f32x4*)(d2 + 32) = o2;
.LBB0_725:
	v_or_b32_e32 v161, s21, v200
	v_lshlrev_b32_e32 v186, 2, v161
	v_mov_b32_e32 v187, v143
	v_lshl_add_u64 v[184:185], v[184:185], 0, v[186:187]
	s_mov_b64 s[100:101], exec
	s_and_b64 exec, exec, s[98:99]
	global_store_dwordx4 v[184:185], v[134:137], off
	global_store_dwordx4 v[184:185], v[130:133], off offset:128
	s_mov_b64 exec, s[100:101]
	s_mov_b64 s[98:99], -1
	s_and_saveexec_b64 s[86:87], s[84:85]
	s_cbranch_execz .LBB0_727
	v_lshl_add_u64 v[184:185], s[40:41], 0, v[164:165]
	v_lshl_add_u64 v[184:185], v[142:143], 2, v[184:185]
	v_lshl_add_u64 v[184:185], v[184:185], 0, v[186:187]
	global_store_dwordx4 v[184:185], v[134:137], off
	global_store_dwordx4 v[184:185], v[130:133], off offset:128

;     DI void operator()(const f32x4 (&acc)[2][2][4][2], const pg8::Unit& u, int wr, int wc, int fr, int fq) const {
;     ...
;                         const int br = which >> 1, kvsel = which & 1;
;                         const int inrow = kvsel * 256 + hh * 64 + dlo;
;                         float* dst;
;                         if (br == 0) dst = out + (samp ? O_CMPS + (size_t)srow * 512 : O_CMPP + (size_t)row * 512);
;                         else if (br == 1) dst = out + (samp ? O_SLCS + (size_t)srow * 512 : O_SLCP + (size_t)row * 512);
;                         else dst = samp ? out + O_WINS + ((size_t)(srow >> 3) * 512 + 504 + (srow & 7)) * 512 : winrows + (size_t)row * 512;
.LBB0_739:
	s_and_b64 vcc, exec, s[8:9]
	s_cbranch_vccnz .LBB0_759
	s_and_b64 vcc, exec, s[6:7]
	s_mov_b64 s[86:87], -1
	s_cbranch_vccnz .LBB0_750
	s_andn2_b64 vcc, exec, s[72:73]
	s_cbranch_vccnz .LBB0_747
	s_and_saveexec_b64 s[86:87], s[10:11]
	s_xor_b64 s[10:11], exec, s[86:87]
	s_mov_b64 s[98:99], s[10:11]
	s_cbranch_execz .LBB0_744
	v_readlane_b32 s30, v254, 17
	v_readlane_b32 s31, v254, 18
	s_nop 1
	v_lshl_add_u64 v[170:171], s[30:31], 0, v[182:183]

;     DI void operator()(const f32x4 (&acc)[2][2][4][2], const pg8::Unit& u, int wr, int wc, int fr, int fq) const {
;     ...
;                         if (br == 0) dst = out + (samp ? O_CMPS + (size_t)srow * 512 : O_CMPP + (size_t)row * 512);
;                         else if (br == 1) dst = out + (samp ? O_SLCS + (size_t)srow * 512 : O_SLCP + (size_t)row * 512);
;                         else dst = samp ? out + O_WINS + ((size_t)(srow >> 3) * 512 + 504 + (srow & 7)) * 512 : winrows + (size_t)row * 512;
;                         *(f32x4*)(dst + inrow) = o1; *(f32x4*)(dst + inrow + 32) = o2;
;                         if (br == 2 && !samp && (row & (TT - 1)) >= TT - 512) {
;                             float* d2 = out + O_WINP + ((size_t)(row >> 11) * 512 + (row & (TT - 1)) - (TT - 512)) * 512 + inrow;
;                             *(f32x4*)d2 = o1; *(f32x4*)(d2 + 32) = o2;
.LBB0_752:
	v_or_b32_e32 v161, s28, v200
	v_lshlrev_b32_e32 v166, 2, v161
	v_mov_b32_e32 v167, v143
	v_lshl_add_u64 v[168:169], v[170:171], 0, v[166:167]
	s_mov_b64 s[100:101], exec
	s_and_b64 exec, exec, s[98:99]
	global_store_dwordx4 v[168:169], v[134:137], off
	global_store_dwordx4 v[168:169], v[130:133], off offset:128
	s_mov_b64 exec, s[100:101]
	s_mov_b64 s[98:99], -1
	s_and_saveexec_b64 s[2:3], s[84:85]
	s_cbranch_execz .LBB0_754
	v_lshl_add_u64 v[168:169], s[40:41], 0, v[164:165]
	v_lshl_add_u64 v[168:169], v[142:143], 2, v[168:169]
	v_lshl_add_u64 v[166:167], v[168:169], 0, v[166:167]
	global_store_dwordx4 v[166:167], v[134:137], off
	global_store_dwordx4 v[166:167], v[130:133], off offset:128

; DI unsigned pk2(float lo, float hi) { f32x2 v = {lo, hi}; bf16x2_t b = __builtin_convertvector(v, bf16x2_t); return __builtin_bit_cast(unsigned, b); }
;     DI void operator()(const f32x4 (&acc)[2][2][4][2], const pg8::Unit& u, int wr, int wc, int fr, int fq) const {
;     ...
;                 const int row = row0 + ai * 128 + m * 16;
;                 const bool samp = row >= MP;
;                 const int srow = row - MP;
;                 const int pos = samp ? (TT + (srow & 7)) : (row & (TT - 1));
;                 float cs[4], sn[4];
; #pragma unroll
;                 for (int i = 0; i < 4; ++i) { float rev = (float)pos * frev[i]; rev = rev - floorf(rev); cs[i] = __builtin_amdgcn_cosf(rev); sn[i] = __builtin_amdgcn_sinf(rev); }
; #pragma unroll
;                 for (int bj = 0; bj < 2; ++bj) {
;                     f32x4 x1 = acc[ai][bj][m][0], x2 = acc[ai][bj][m][1], o1, o2;
;                     if (dorope) {
; #pragma unroll
;                         for (int i = 0; i < 4; ++i) { o1[i] = x1[i] * cs[i] - x2[i] * sn[i]; o2[i] = x2[i] * cs[i] + x1[i] * sn[i]; }
;                     } else { o1 = x1; o2 = x2; }
;                     const int hh = 2 * bj + (wc >> 1);
;                     if (pn < 16) {
;                         const int head = (pn - 12) * 4 + hh;
;                         bf16* q = nq + (size_t)row * 1024 + head * 64 + dlo;
;                         u32x2 w1, w2; w1.x = pk2(o1[0] * 0.125f, o1[1] * 0.125f); w1.y = pk2(o1[2] * 0.125f, o1[3] * 0.125f); w2.x = pk2(o2[0] * 0.125f, o2[1] * 0.125f); w2.y = pk2(o2[2] * 0.125f, o2[3] * 0.125f);
;                         *(u32x2*)q = w1; *(u32x2*)(q + 32) = w2;
;                     } else {
;                         const int br = which >> 1, kvsel = which & 1;
;                         const int inrow = kvsel * 256 + hh * 64 + dlo;
;                         float* dst;
;                         if (br == 0) dst = out + (samp ? O_CMPS + (size_t)srow * 512 : O_CMPP + (size_t)row * 512);
;                         else if (br == 1) dst = out + (samp ? O_SLCS + (size_t)srow * 512 : O_SLCP + (size_t)row * 512);
;                         else dst = samp ? out + O_WINS + ((size_t)(srow >> 3) * 512 + 504 + (srow & 7)) * 512 : winrows + (size_t)row * 512;
.LBB0_765:
	v_add_u32_e32 v166, 0xffffc090, v158
	v_lshrrev_b32_e32 v142, 3, v166
	v_lshlrev_b64 v[178:179], 18, v[142:143]
	v_cmp_lt_u32_e32 vcc, s13, v161
	v_lshlrev_b32_e32 v142, 9, v161
	v_lshlrev_b32_e32 v161, 6, v184
	v_ashrrev_i32_e32 v185, 31, v184
	v_mov_b32_e32 v167, v143
	v_and_b32_e32 v202, 0x1f7c0, v161
	v_lshrrev_b32_e32 v161, 4, v184
	v_lshlrev_b64 v[168:169], 9, v[184:185]
	v_lshlrev_b64 v[186:187], 9, v[166:167]
	s_nor_b64 s[80:81], s[78:79], s[2:3]
	v_and_b32_e32 v161, 0x7d, v161
	v_lshlrev_b64 v[182:183], 11, v[184:185]
	v_or_b32_e32 v178, v178, v148
	v_lshl_add_u64 v[170:171], v[168:169], 0, s[50:51]
	v_lshl_add_u64 v[172:173], v[186:187], 0, s[52:53]
	v_lshl_add_u64 v[166:167], v[168:169], 0, s[54:55]
	v_lshl_add_u64 v[168:169], v[186:187], 0, s[56:57]
	s_and_b64 s[84:85], s[80:81], vcc
	s_nor_b64 s[82:83], s[76:77], s[2:3]
	s_nor_b64 s[80:81], s[74:75], s[2:3]
	s_and_b64 vcc, exec, s[8:9]
	v_or_b32_e32 v201, s65, v161
	s_cbranch_vccnz .LBB0_785
	s_and_b64 vcc, exec, s[6:7]
	s_mov_b64 s[86:87], -1
	s_cbranch_vccnz .LBB0_776
	s_andn2_b64 vcc, exec, s[72:73]
	s_cbranch_vccnz .LBB0_773
	s_and_saveexec_b64 s[86:87], s[10:11]
	s_xor_b64 s[86:87], exec, s[86:87]
	s_mov_b64 s[98:99], s[86:87]
	s_cbranch_execz .LBB0_770
	v_readlane_b32 s30, v254, 17
	v_readlane_b32 s31, v254, 18
	s_nop 1
	v_lshl_add_u64 v[184:185], s[30:31], 0, v[182:183]

;     DI void operator()(const f32x4 (&acc)[2][2][4][2], const pg8::Unit& u, int wr, int wc, int fr, int fq) const {
;     ...
;                         const int br = which >> 1, kvsel = which & 1;
;                         const int inrow = kvsel * 256 + hh * 64 + dlo;
;                         float* dst;
;                         if (br == 0) dst = out + (samp ? O_CMPS + (size_t)srow * 512 : O_CMPP + (size_t)row * 512);
;                         else if (br == 1) dst = out + (samp ? O_SLCS + (size_t)srow * 512 : O_SLCP + (size_t)row * 512);
;                         else dst = samp ? out + O_WINS + ((size_t)(srow >> 3) * 512 + 504 + (srow & 7)) * 512 : winrows + (size_t)row * 512;
.LBB0_792:
	s_and_b64 vcc, exec, s[8:9]
	s_cbranch_vccnz .LBB0_812
	s_and_b64 vcc, exec, s[6:7]
	s_mov_b64 s[86:87], -1
	s_cbranch_vccnz .LBB0_803
	s_andn2_b64 vcc, exec, s[72:73]
	s_cbranch_vccnz .LBB0_800
	s_and_saveexec_b64 s[86:87], s[10:11]
	s_xor_b64 s[10:11], exec, s[86:87]
	s_mov_b64 s[98:99], s[10:11]
	s_cbranch_execz .LBB0_797
	v_readlane_b32 s30, v254, 17
	v_readlane_b32 s31, v254, 18
	s_nop 1
	v_lshl_add_u64 v[174:175], s[30:31], 0, v[182:183]

;     DI void operator()(const f32x4 (&acc)[2][2][4][2], const pg8::Unit& u, int wr, int wc, int fr, int fq) const {
;     ...
;                         if (br == 0) dst = out + (samp ? O_CMPS + (size_t)srow * 512 : O_CMPP + (size_t)row * 512);
;                         else if (br == 1) dst = out + (samp ? O_SLCS + (size_t)srow * 512 : O_SLCP + (size_t)row * 512);
;                         else dst = samp ? out + O_WINS + ((size_t)(srow >> 3) * 512 + 504 + (srow & 7)) * 512 : winrows + (size_t)row * 512;
;                         *(f32x4*)(dst + inrow) = o1; *(f32x4*)(dst + inrow + 32) = o2;
;                         if (br == 2 && !samp && (row & (TT - 1)) >= TT - 512) {
;                             float* d2 = out + O_WINP + ((size_t)(row >> 11) * 512 + (row & (TT - 1)) - (TT - 512)) * 512 + inrow;
;                             *(f32x4*)d2 = o1; *(f32x4*)(d2 + 32) = o2;
.LBB0_805:
	v_or_b32_e32 v161, s28, v200
	v_lshlrev_b32_e32 v166, 2, v161
	v_mov_b32_e32 v167, v143
	v_lshl_add_u64 v[168:169], v[174:175], 0, v[166:167]
	s_mov_b64 s[100:101], exec
	s_and_b64 exec, exec, s[98:99]
	global_store_dwordx4 v[168:169], v[134:137], off
	global_store_dwordx4 v[168:169], v[130:133], off offset:128
	s_mov_b64 exec, s[100:101]
	s_mov_b64 s[98:99], -1
	s_and_saveexec_b64 s[2:3], s[84:85]
	s_cbranch_execz .LBB0_807
	v_lshl_add_u64 v[168:169], s[40:41], 0, v[164:165]
	v_lshl_add_u64 v[168:169], v[142:143], 2, v[168:169]
	v_lshl_add_u64 v[166:167], v[168:169], 0, v[166:167]
	global_store_dwordx4 v[166:167], v[134:137], off
	global_store_dwordx4 v[166:167], v[130:133], off offset:128

; DI unsigned pk2(float lo, float hi) { f32x2 v = {lo, hi}; bf16x2_t b = __builtin_convertvector(v, bf16x2_t); return __builtin_bit_cast(unsigned, b); }
;     DI void operator()(const f32x4 (&acc)[2][2][4][2], const pg8::Unit& u, int wr, int wc, int fr, int fq) const {
;     ...
;                 const int row = row0 + ai * 128 + m * 16;
;                 const bool samp = row >= MP;
;                 const int srow = row - MP;
;                 const int pos = samp ? (TT + (srow & 7)) : (row & (TT - 1));
;                 float cs[4], sn[4];
; #pragma unroll
;                 for (int i = 0; i < 4; ++i) { float rev = (float)pos * frev[i]; rev = rev - floorf(rev); cs[i] = __builtin_amdgcn_cosf(rev); sn[i] = __builtin_amdgcn_sinf(rev); }
; #pragma unroll
;                 for (int bj = 0; bj < 2; ++bj) {
;                     f32x4 x1 = acc[ai][bj][m][0], x2 = acc[ai][bj][m][1], o1, o2;
;                     if (dorope) {
; #pragma unroll
;                         for (int i = 0; i < 4; ++i) { o1[i] = x1[i] * cs[i] - x2[i] * sn[i]; o2[i] = x2[i] * cs[i] + x1[i] * sn[i]; }
;                     } else { o1 = x1; o2 = x2; }
;                     const int hh = 2 * bj + (wc >> 1);
;                     if (pn < 16) {
;                         const int head = (pn - 12) * 4 + hh;
;                         bf16* q = nq + (size_t)row * 1024 + head * 64 + dlo;
;                         u32x2 w1, w2; w1.x = pk2(o1[0] * 0.125f, o1[1] * 0.125f); w1.y = pk2(o1[2] * 0.125f, o1[3] * 0.125f); w2.x = pk2(o2[0] * 0.125f, o2[1] * 0.125f); w2.y = pk2(o2[2] * 0.125f, o2[3] * 0.125f);
;                         *(u32x2*)q = w1; *(u32x2*)(q + 32) = w2;
;                     } else {
;                         const int br = which >> 1, kvsel = which & 1;
;                         const int inrow = kvsel * 256 + hh * 64 + dlo;
;                         float* dst;
;                         if (br == 0) dst = out + (samp ? O_CMPS + (size_t)srow * 512 : O_CMPP + (size_t)row * 512);
;                         else if (br == 1) dst = out + (samp ? O_SLCS + (size_t)srow * 512 : O_SLCP + (size_t)row * 512);
;                         else dst = samp ? out + O_WINS + ((size_t)(srow >> 3) * 512 + 504 + (srow & 7)) * 512 : winrows + (size_t)row * 512;
.LBB0_818:
	v_add_u32_e32 v166, 0xffffc0a0, v158
	v_lshrrev_b32_e32 v142, 3, v166
	v_lshlrev_b64 v[178:179], 18, v[142:143]
	v_cmp_lt_u32_e32 vcc, s13, v161
	v_lshlrev_b32_e32 v142, 9, v161
	v_lshlrev_b32_e32 v161, 6, v184
	v_ashrrev_i32_e32 v185, 31, v184
	v_mov_b32_e32 v167, v143
	v_and_b32_e32 v202, 0x1fbc0, v161
	v_lshrrev_b32_e32 v161, 4, v184
	v_lshlrev_b64 v[168:169], 9, v[184:185]
	v_lshlrev_b64 v[186:187], 9, v[166:167]
	s_nor_b64 s[80:81], s[78:79], s[2:3]
	v_and_b32_e32 v161, 0x7e, v161
	v_lshlrev_b64 v[182:183], 11, v[184:185]
	v_or_b32_e32 v178, v178, v148
	v_lshl_add_u64 v[170:171], v[168:169], 0, s[50:51]
	v_lshl_add_u64 v[172:173], v[186:187], 0, s[52:53]
	v_lshl_add_u64 v[166:167], v[168:169], 0, s[54:55]
	v_lshl_add_u64 v[168:169], v[186:187], 0, s[56:57]
	s_and_b64 s[84:85], s[80:81], vcc
	s_nor_b64 s[82:83], s[76:77], s[2:3]
	s_nor_b64 s[80:81], s[74:75], s[2:3]
	s_and_b64 vcc, exec, s[8:9]
	v_or_b32_e32 v201, s65, v161
	s_cbranch_vccnz .LBB0_838
	s_and_b64 vcc, exec, s[6:7]
	s_mov_b64 s[86:87], -1
	s_cbranch_vccnz .LBB0_829
	s_andn2_b64 vcc, exec, s[72:73]
	s_cbranch_vccnz .LBB0_826
	s_and_saveexec_b64 s[86:87], s[10:11]
	s_xor_b64 s[86:87], exec, s[86:87]
	s_mov_b64 s[98:99], s[86:87]
	s_cbranch_execz .LBB0_823
	v_readlane_b32 s30, v254, 17
	v_readlane_b32 s31, v254, 18
	s_nop 1
	v_lshl_add_u64 v[184:185], s[30:31], 0, v[182:183]

; DI unsigned pk2(float lo, float hi) { f32x2 v = {lo, hi}; bf16x2_t b = __builtin_convertvector(v, bf16x2_t); return __builtin_bit_cast(unsigned, b); }
;     DI void operator()(const f32x4 (&acc)[2][2][4][2], const pg8::Unit& u, int wr, int wc, int fr, int fq) const {
;     ...
;                 const int row = row0 + ai * 128 + m * 16;
;                 const bool samp = row >= MP;
;                 const int srow = row - MP;
;                 const int pos = samp ? (TT + (srow & 7)) : (row & (TT - 1));
;                 float cs[4], sn[4];
; #pragma unroll
;                 for (int i = 0; i < 4; ++i) { float rev = (float)pos * frev[i]; rev = rev - floorf(rev); cs[i] = __builtin_amdgcn_cosf(rev); sn[i] = __builtin_amdgcn_sinf(rev); }
; #pragma unroll
;                 for (int bj = 0; bj < 2; ++bj) {
;                     f32x4 x1 = acc[ai][bj][m][0], x2 = acc[ai][bj][m][1], o1, o2;
;                     if (dorope) {
; #pragma unroll
;                         for (int i = 0; i < 4; ++i) { o1[i] = x1[i] * cs[i] - x2[i] * sn[i]; o2[i] = x2[i] * cs[i] + x1[i] * sn[i]; }
;                     } else { o1 = x1; o2 = x2; }
;                     const int hh = 2 * bj + (wc >> 1);
;                     if (pn < 16) {
;                         const int head = (pn - 12) * 4 + hh;
;                         bf16* q = nq + (size_t)row * 1024 + head * 64 + dlo;
;                         u32x2 w1, w2; w1.x = pk2(o1[0] * 0.125f, o1[1] * 0.125f); w1.y = pk2(o1[2] * 0.125f, o1[3] * 0.125f); w2.x = pk2(o2[0] * 0.125f, o2[1] * 0.125f); w2.y = pk2(o2[2] * 0.125f, o2[3] * 0.125f);
;                         *(u32x2*)q = w1; *(u32x2*)(q + 32) = w2;
;                     } else {
;                         const int br = which >> 1, kvsel = which & 1;
;                         const int inrow = kvsel * 256 + hh * 64 + dlo;
;                         float* dst;
;                         if (br == 0) dst = out + (samp ? O_CMPS + (size_t)srow * 512 : O_CMPP + (size_t)row * 512);
;                         else if (br == 1) dst = out + (samp ? O_SLCS + (size_t)srow * 512 : O_SLCP + (size_t)row * 512);
;                         else dst = samp ? out + O_WINS + ((size_t)(srow >> 3) * 512 + 504 + (srow & 7)) * 512 : winrows + (size_t)row * 512;
.LBB0_871:
	v_add_u32_e32 v166, 0xffffc0b0, v158
	v_lshrrev_b32_e32 v142, 3, v166
	v_ashrrev_i32_e32 v185, 31, v184
	v_lshlrev_b64 v[178:179], 18, v[142:143]
	v_mov_b32_e32 v167, v143
	v_cmp_lt_u32_e32 vcc, s13, v161
	v_lshlrev_b32_e32 v142, 9, v161
	v_lshlrev_b32_e32 v161, 6, v184
	v_lshlrev_b64 v[168:169], 9, v[184:185]
	v_lshlrev_b64 v[186:187], 9, v[166:167]
	s_nor_b64 s[78:79], s[78:79], s[2:3]
	v_and_b32_e32 v202, 0x1ffc0, v161
	v_bfe_u32 v161, v184, 4, 7
	v_lshlrev_b64 v[180:181], 11, v[184:185]
	v_or_b32_e32 v178, v178, v148
	v_lshl_add_u64 v[170:171], v[168:169], 0, s[50:51]
	v_lshl_add_u64 v[172:173], v[186:187], 0, s[52:53]
	v_lshl_add_u64 v[166:167], v[168:169], 0, s[54:55]
	v_lshl_add_u64 v[168:169], v[186:187], 0, s[56:57]
	s_and_b64 s[78:79], s[78:79], vcc
	s_nor_b64 s[76:77], s[76:77], s[2:3]
	s_nor_b64 s[74:75], s[74:75], s[2:3]
	s_and_b64 vcc, exec, s[8:9]
	v_or_b32_e32 v201, s65, v161
	s_cbranch_vccnz .LBB0_891
	s_and_b64 vcc, exec, s[6:7]
	s_mov_b64 s[80:81], -1
	s_cbranch_vccnz .LBB0_882
	s_andn2_b64 vcc, exec, s[72:73]
	s_cbranch_vccnz .LBB0_879
	s_and_saveexec_b64 s[80:81], s[10:11]
	s_xor_b64 s[80:81], exec, s[80:81]
	s_mov_b64 s[98:99], s[80:81]
	s_cbranch_execz .LBB0_876
	v_readlane_b32 s30, v254, 17
	v_readlane_b32 s31, v254, 18
	s_nop 1
	v_lshl_add_u64 v[184:185], s[30:31], 0, v[180:181]

;     DI void operator()(const f32x4 (&acc)[2][2][4][2], const pg8::Unit& u, int wr, int wc, int fr, int fq) const {
;     ...
;                         if (br == 0) dst = out + (samp ? O_CMPS + (size_t)srow * 512 : O_CMPP + (size_t)row * 512);
;                         else if (br == 1) dst = out + (samp ? O_SLCS + (size_t)srow * 512 : O_SLCP + (size_t)row * 512);
;                         else dst = samp ? out + O_WINS + ((size_t)(srow >> 3) * 512 + 504 + (srow & 7)) * 512 : winrows + (size_t)row * 512;
;                         *(f32x4*)(dst + inrow) = o1; *(f32x4*)(dst + inrow + 32) = o2;
;                         if (br == 2 && !samp && (row & (TT - 1)) >= TT - 512) {
;                             float* d2 = out + O_WINP + ((size_t)(row >> 11) * 512 + (row & (TT - 1)) - (TT - 512)) * 512 + inrow;
;                             *(f32x4*)d2 = o1; *(f32x4*)(d2 + 32) = o2;
.LBB0_884:
	v_or_b32_e32 v161, s21, v200
	v_lshlrev_b32_e32 v186, 2, v161
	v_mov_b32_e32 v187, v143
	v_lshl_add_u64 v[184:185], v[184:185], 0, v[186:187]
	s_mov_b64 s[100:101], exec
	s_and_b64 exec, exec, s[98:99]
	global_store_dwordx4 v[184:185], v[134:137], off
	global_store_dwordx4 v[184:185], v[130:133], off offset:128
	s_mov_b64 exec, s[100:101]
	s_mov_b64 s[98:99], -1
	s_and_saveexec_b64 s[80:81], s[78:79]
	s_cbranch_execz .LBB0_886
	v_lshl_add_u64 v[184:185], s[40:41], 0, v[164:165]
	v_lshl_add_u64 v[184:185], v[142:143], 2, v[184:185]
	v_lshl_add_u64 v[184:185], v[184:185], 0, v[186:187]
	global_store_dwordx4 v[184:185], v[134:137], off
	global_store_dwordx4 v[184:185], v[130:133], off offset:128

;     DI void operator()(const f32x4 (&acc)[2][2][4][2], const pg8::Unit& u, int wr, int wc, int fr, int fq) const {
;     ...
;                         const int br = which >> 1, kvsel = which & 1;
;                         const int inrow = kvsel * 256 + hh * 64 + dlo;
;                         float* dst;
;                         if (br == 0) dst = out + (samp ? O_CMPS + (size_t)srow * 512 : O_CMPP + (size_t)row * 512);
;                         else if (br == 1) dst = out + (samp ? O_SLCS + (size_t)srow * 512 : O_SLCP + (size_t)row * 512);
;                         else dst = samp ? out + O_WINS + ((size_t)(srow >> 3) * 512 + 504 + (srow & 7)) * 512 : winrows + (size_t)row * 512;
.LBB0_898:
	v_readlane_b32 s80, v253, 61
	s_and_b64 vcc, exec, s[8:9]
	s_mov_b32 s96, s22
	v_readlane_b32 s81, v253, 62
	s_cbranch_vccnz .LBB0_918
	s_and_b64 vcc, exec, s[6:7]
	s_mov_b64 s[4:5], -1
	s_cbranch_vccnz .LBB0_909
	s_andn2_b64 vcc, exec, s[72:73]
	s_cbranch_vccnz .LBB0_906
	s_and_saveexec_b64 s[4:5], s[10:11]
	s_xor_b64 s[4:5], exec, s[4:5]
	s_mov_b64 s[98:99], s[4:5]
	s_cbranch_execz .LBB0_903
	v_readlane_b32 s6, v254, 17
	v_readlane_b32 s7, v254, 18
	s_nop 1
	v_lshl_add_u64 v[174:175], s[6:7], 0, v[180:181]

;     DI void operator()(const f32x4 (&acc)[2][2][4][2], const pg8::Unit& u, int wr, int wc, int fr, int fq) const {
;     ...
;                         if (br == 0) dst = out + (samp ? O_CMPS + (size_t)srow * 512 : O_CMPP + (size_t)row * 512);
;                         else if (br == 1) dst = out + (samp ? O_SLCS + (size_t)srow * 512 : O_SLCP + (size_t)row * 512);
;                         else dst = samp ? out + O_WINS + ((size_t)(srow >> 3) * 512 + 504 + (srow & 7)) * 512 : winrows + (size_t)row * 512;
;                         *(f32x4*)(dst + inrow) = o1; *(f32x4*)(dst + inrow + 32) = o2;
;                         if (br == 2 && !samp && (row & (TT - 1)) >= TT - 512) {
;                             float* d2 = out + O_WINP + ((size_t)(row >> 11) * 512 + (row & (TT - 1)) - (TT - 512)) * 512 + inrow;
;                             *(f32x4*)d2 = o1; *(f32x4*)(d2 + 32) = o2;
.LBB0_911:
	v_or_b32_e32 v161, s28, v200
	v_lshlrev_b32_e32 v166, 2, v161
	v_mov_b32_e32 v167, v143
	v_lshl_add_u64 v[168:169], v[174:175], 0, v[166:167]
	s_mov_b64 s[100:101], exec
	s_and_b64 exec, exec, s[98:99]
	global_store_dwordx4 v[168:169], v[134:137], off
	global_store_dwordx4 v[168:169], v[130:133], off offset:128
	s_mov_b64 exec, s[100:101]
	s_mov_b64 s[98:99], -1
	s_and_saveexec_b64 s[2:3], s[78:79]
	s_cbranch_execz .LBB0_913
	v_lshl_add_u64 v[164:165], s[40:41], 0, v[164:165]
	v_lshl_add_u64 v[164:165], v[142:143], 2, v[164:165]
	v_lshl_add_u64 v[164:165], v[164:165], 0, v[166:167]
	global_store_dwordx4 v[164:165], v[134:137], off
	global_store_dwordx4 v[164:165], v[130:133], off offset:128

; __global__ void __launch_bounds__(NWAVES * 64, 2) hybrid_fwd(Args args) {
	.amdhsa_kernel _Z10hybrid_fwd4Args
		.amdhsa_group_segment_fixed_size 0
		.amdhsa_private_segment_fixed_size 0
		.amdhsa_kernarg_size 448
		.amdhsa_user_sgpr_count 2
		.amdhsa_user_sgpr_dispatch_ptr 0
		.amdhsa_user_sgpr_queue_ptr 0
		.amdhsa_user_sgpr_kernarg_segment_ptr 1
		.amdhsa_user_sgpr_dispatch_id 0
		.amdhsa_user_sgpr_kernarg_preload_length 0
		.amdhsa_user_sgpr_kernarg_preload_offset 0
		.amdhsa_user_sgpr_private_segment_size 0
		.amdhsa_uses_dynamic_stack 0
		.amdhsa_enable_private_segment 0
		.amdhsa_system_sgpr_workgroup_id_x 1
		.amdhsa_system_sgpr_workgroup_id_y 0
		.amdhsa_system_sgpr_workgroup_id_z 0
		.amdhsa_system_sgpr_workgroup_info 0
		.amdhsa_system_vgpr_workitem_id 0
		.amdhsa_next_free_vgpr 255
		.amdhsa_next_free_sgpr 102
		.amdhsa_accum_offset 256
		.amdhsa_reserve_vcc 1
		.amdhsa_float_round_mode_32 0
		.amdhsa_float_round_mode_16_64 0
		.amdhsa_float_denorm_mode_32 3
		.amdhsa_float_denorm_mode_16_64 3
		.amdhsa_dx10_clamp 1
		.amdhsa_ieee_mode 1
		.amdhsa_fp16_overflow 0
		.amdhsa_tg_split 0
		.amdhsa_exception_fp_ieee_invalid_op 0
		.amdhsa_exception_fp_denorm_src 0
		.amdhsa_exception_fp_ieee_div_zero 0
		.amdhsa_exception_fp_ieee_overflow 0
		.amdhsa_exception_fp_ieee_underflow 0
		.amdhsa_exception_fp_ieee_inexact 0
		.amdhsa_exception_int_div_zero 0
	.end_amdhsa_kernel

; __global__ void __launch_bounds__(NWAVES * 64, 2) hybrid_fwd(Args args) {
amdhsa.kernels:
  - .agpr_count:     0
    .args:
      - .offset:         0
        .size:           192
        .value_kind:     by_value
      - .offset:         192
        .size:           4
        .value_kind:     hidden_block_count_x
      - .offset:         196
        .size:           4
        .value_kind:     hidden_block_count_y
      - .offset:         200
        .size:           4
        .value_kind:     hidden_block_count_z
      - .offset:         204
        .size:           2
        .value_kind:     hidden_group_size_x
      - .offset:         206
        .size:           2
        .value_kind:     hidden_group_size_y
      - .offset:         208
        .size:           2
        .value_kind:     hidden_group_size_z
      - .offset:         210
        .size:           2
        .value_kind:     hidden_remainder_x
      - .offset:         212
        .size:           2
        .value_kind:     hidden_remainder_y
      - .offset:         214
        .size:           2
        .value_kind:     hidden_remainder_z
      - .offset:         232
        .size:           8
        .value_kind:     hidden_global_offset_x
      - .offset:         240
        .size:           8
        .value_kind:     hidden_global_offset_y
      - .offset:         248
        .size:           8
        .value_kind:     hidden_global_offset_z
      - .offset:         256
        .size:           2
        .value_kind:     hidden_grid_dims
      - .offset:         312
        .size:           4
        .value_kind:     hidden_dynamic_lds_size
    .group_segment_fixed_size: 0
    .kernarg_segment_align: 8
    .kernarg_segment_size: 448
    .language:       OpenCL C
    .language_version:
      - 2
      - 0
    .max_flat_workgroup_size: 512
    .name:           _Z10hybrid_fwd4Args
    .private_segment_fixed_size: 0
    .sgpr_count:     108
    .sgpr_spill_count: 189
    .symbol:         _Z10hybrid_fwd4Args.kd
    .uniform_work_group_size: 1
    .uses_dynamic_stack: false
    .vgpr_count:     255
    .vgpr_spill_count: 0
    .wavefront_size: 64
